# keep norm gamma in registers in P0/P8 row loops (no reload + full drain after each store)
# speedup vs baseline: 1.0080x; 1.0026x over previous
.LBB0_520:
	s_nop 0
	v_readlane_b32 s2, v250, 23
	v_readlane_b32 s3, v250, 24
	s_andn2_b64 vcc, exec, s[2:3]
	s_cbranch_vccnz .LBB0_548
	v_mov_b32_e32 v0, v144
	s_mov_b32 s2, s45
	s_cmp_gt_i32 s2, 3
	v_ashrrev_i32_e32 v95, 6, v0
	v_and_b32_e32 v94, 63, v0
	s_mov_b64 s[0:1], -1
	s_cbranch_scc0 .LBB0_529
	v_readlane_b32 s0, v251, 9
	s_nop 1
	v_mul_lo_u32 v0, v95, s0
	v_add3_u32 v96, s2, -4, v0
	v_cmp_gt_i32_e32 vcc, s25, v96
	s_and_saveexec_b64 s[0:1], vcc
	v_readlane_b32 s6, v251, 15
	v_readlane_b32 s7, v251, 16
	s_mov_b32 s7, 0x800000
	s_mov_b32 s8, 0x3a800000
	s_mov_b32 s10, 0x358637bd
	s_cbranch_execz .LBB0_525
	v_lshlrev_b32_e32 v0, 5, v94
	v_readlane_b32 s4, v252, 51
	v_readlane_b32 s3, v251, 10
	v_lshl_add_u64 v[78:79], s[82:83], 0, v[0:1]
	global_load_dwordx4 v[170:173], v[78:79], off
	global_load_dwordx4 v[174:177], v[78:79], off offset:16
	global_load_dwordx4 v[178:181], v[78:79], off offset:2048
	global_load_dwordx4 v[182:185], v[78:79], off offset:2064
	s_waitcnt vmcnt(0) lgkmcnt(0)
	v_lshlrev_b32_e32 v2, 4, v94
	v_mov_b32_e32 v3, v1
	v_readlane_b32 s5, v252, 52
	v_lshl_add_u64 v[84:85], s[84:85], 0, v[0:1]
	v_mul_lo_u32 v0, s3, v95
	s_lshl_b32 s3, s2, 2
	v_lshl_add_u64 v[80:81], s[4:5], 0, v[2:3]
	v_lshl_add_u64 v[82:83], s[78:79], 0, v[2:3]
	v_add3_u32 v86, v0, s3, -15
	s_mov_b64 s[4:5], 0
	v_mov_b32_e32 v0, v96
.LBB0_524:
	v_ashrrev_i32_e32 v87, 31, v86
	v_lshlrev_b64 v[4:5], 6, v[86:87]
	v_lshlrev_b64 v[6:7], 11, v[86:87]
	v_lshl_add_u64 v[4:5], s[66:67], 0, v[4:5]
	v_lshl_add_u64 v[12:13], v[80:81], 0, v[6:7]
	v_lshl_add_u64 v[6:7], v[82:83], 0, v[6:7]
	global_load_dwordx4 v[102:105], v[4:5], off offset:32
	global_load_dwordx4 v[106:109], v[4:5], off offset:48
	global_load_dwordx4 v[110:113], v[4:5], off
	global_load_dwordx4 v[114:117], v[4:5], off offset:16
	global_load_dwordx4 v[118:121], v[12:13], off
	global_load_dwordx4 v[70:73], v[12:13], off offset:1024
	global_load_dwordx4 v[74:77], v[6:7], off
	global_load_dwordx4 v[66:69], v[6:7], off offset:1024
	v_add_u32_e32 v2, -1, v86
	v_add_u32_e32 v90, 1, v86
	v_add_u32_e32 v88, 2, v86
	v_ashrrev_i32_e32 v3, 31, v2
	v_ashrrev_i32_e32 v91, 31, v90
	v_ashrrev_i32_e32 v89, 31, v88
	v_lshlrev_b64 v[8:9], 6, v[2:3]
	v_lshlrev_b64 v[10:11], 11, v[2:3]
	v_lshlrev_b64 v[14:15], 6, v[90:91]
	v_lshlrev_b64 v[16:17], 11, v[90:91]
	v_lshlrev_b64 v[18:19], 6, v[88:89]
	v_lshlrev_b64 v[20:21], 11, v[88:89]
	v_lshlrev_b64 v[2:3], 12, v[2:3]
	v_lshl_add_u64 v[8:9], s[66:67], 0, v[8:9]
	v_lshl_add_u64 v[22:23], v[80:81], 0, v[10:11]
	v_lshl_add_u64 v[10:11], v[82:83], 0, v[10:11]
	v_lshl_add_u64 v[4:5], s[66:67], 0, v[14:15]
	v_lshl_add_u64 v[6:7], v[80:81], 0, v[16:17]
	v_lshl_add_u64 v[12:13], v[82:83], 0, v[16:17]
	v_lshl_add_u64 v[14:15], s[66:67], 0, v[18:19]
	v_lshl_add_u64 v[16:17], v[80:81], 0, v[20:21]
	v_lshl_add_u64 v[142:143], v[82:83], 0, v[20:21]
	v_lshl_add_u64 v[166:167], v[84:85], 0, v[2:3]
	global_load_dwordx4 v[122:125], v[8:9], off
	global_load_dwordx4 v[126:129], v[8:9], off offset:16
	global_load_dwordx4 v[130:133], v[8:9], off offset:32
	global_load_dwordx4 v[134:137], v[8:9], off offset:48
	global_load_dwordx4 v[138:141], v[22:23], off
	global_load_dwordx4 v[154:157], v[10:11], off
	global_load_dwordx4 v[158:161], v[22:23], off offset:1024
	global_load_dwordx4 v[162:165], v[10:11], off offset:1024
	global_load_dwordx4 v[58:61], v[4:5], off offset:32
	global_load_dwordx4 v[34:37], v[4:5], off offset:48
	global_load_dwordx4 v[62:65], v[4:5], off
	global_load_dwordx4 v[38:41], v[4:5], off offset:16
	global_load_dwordx4 v[30:33], v[6:7], off
	global_load_dwordx4 v[22:25], v[6:7], off offset:1024
	global_load_dwordx4 v[26:29], v[12:13], off
	global_load_dwordx4 v[18:21], v[12:13], off offset:1024
	global_load_dwordx4 v[50:53], v[14:15], off offset:32
	global_load_dwordx4 v[42:45], v[14:15], off offset:48
	global_load_dwordx4 v[54:57], v[14:15], off
	global_load_dwordx4 v[46:49], v[14:15], off offset:16
	s_nop 0
	global_load_dwordx4 v[10:13], v[16:17], off
	global_load_dwordx4 v[2:5], v[16:17], off offset:1024
	s_nop 0
	global_load_dwordx4 v[14:17], v[142:143], off
	global_load_dwordx4 v[6:9], v[142:143], off offset:1024
	v_mov_b64_e32 v[92:93], s[10:11]
	v_add_u32_e32 v0, s6, v0
	s_waitcnt vmcnt(0)
	v_mov_b32_e32 v142, v110
	v_mov_b32_e32 v143, v114
	v_mov_b32_e32 v114, v111
	v_mov_b32_e32 v110, v112
	v_mov_b32_e32 v111, v116
	v_mov_b32_e32 v116, v113
	v_mov_b32_e32 v112, v102
	v_mov_b32_e32 v113, v106
	v_mov_b32_e32 v106, v103
	v_mov_b32_e32 v102, v104
	v_mov_b32_e32 v103, v108
	v_mov_b32_e32 v108, v105
	v_mov_b32_e32 v104, v122
	v_mov_b32_e32 v105, v126
	v_mov_b32_e32 v126, v123
	v_mov_b32_e32 v122, v124
	v_mov_b32_e32 v123, v128
	v_mov_b32_e32 v128, v125
	v_mov_b32_e32 v124, v130
	v_mov_b32_e32 v125, v134
	v_mov_b32_e32 v134, v131
	v_pk_add_f32 v[114:115], v[142:143], v[114:115]
	v_pk_add_f32 v[104:105], v[104:105], v[126:127]
	v_mov_b32_e32 v130, v132
	v_mov_b32_e32 v131, v136
	v_pk_add_f32 v[106:107], v[112:113], v[106:107]
	v_pk_add_f32 v[112:113], v[124:125], v[134:135]
	v_pk_add_f32 v[110:111], v[110:111], v[114:115]
	v_pk_add_f32 v[104:105], v[122:123], v[104:105]
	v_mov_b32_e32 v136, v133
	v_pk_add_f32 v[102:103], v[102:103], v[106:107]
	v_pk_add_f32 v[106:107], v[130:131], v[112:113]
	v_pk_add_f32 v[110:111], v[116:117], v[110:111]
	v_pk_add_f32 v[104:105], v[128:129], v[104:105]
	v_pk_add_f32 v[102:103], v[108:109], v[102:103]
	v_pk_add_f32 v[106:107], v[136:137], v[106:107]
	v_mov_b32_e32 v108, v110
	v_mov_b32_e32 v109, v104
	v_mov_b32_e32 v104, v111
	v_mov_b32_e32 v110, v102
	v_mov_b32_e32 v111, v106
	v_mov_b32_e32 v106, v103
	v_pk_add_f32 v[102:103], v[108:109], v[104:105]
	v_lshlrev_b32_e32 v168, 16, v154
	v_pk_add_f32 v[102:103], v[102:103], v[110:111]
	v_and_b32_e32 v169, 0xffff0000, v154
	v_pk_add_f32 v[102:103], v[102:103], v[106:107]
	v_lshlrev_b32_e32 v154, 16, v155
	v_pk_fma_f32 v[102:103], v[102:103], s[8:9], v[92:93] op_sel_hi:[1,0,0]
	v_and_b32_e32 v155, 0xffff0000, v155
	v_mul_f32_e32 v97, 0x4b800000, v103
	v_cmp_gt_f32_e32 vcc, s7, v103
	v_lshlrev_b32_e32 v132, 16, v138
	v_and_b32_e32 v133, 0xffff0000, v138
	v_cndmask_b32_e32 v97, v103, v97, vcc
	v_rsq_f32_e32 v97, v97
	v_lshlrev_b32_e32 v138, 16, v139
	v_and_b32_e32 v139, 0xffff0000, v139
	v_lshlrev_b32_e32 v110, 16, v156
	v_mul_f32_e32 v103, 0x45800000, v97
	v_cndmask_b32_e32 v104, v97, v103, vcc
	v_pk_mul_f32 v[106:107], v[104:105], v[168:169] op_sel_hi:[0,1]
	v_pk_mul_f32 v[108:109], v[104:105], v[154:155] op_sel_hi:[0,1]
	v_pk_fma_f32 v[100:101], v[108:109], v[172:173], v[138:139]
	v_pk_fma_f32 v[98:99], v[106:107], v[170:171], v[132:133]
	global_store_dwordx4 v[166:167], v[98:101], off
	v_and_b32_e32 v111, 0xffff0000, v156
	v_lshlrev_b32_e32 v112, 16, v157
	v_and_b32_e32 v113, 0xffff0000, v157
	v_lshlrev_b32_e32 v106, 16, v140
	v_and_b32_e32 v107, 0xffff0000, v140
	v_lshlrev_b32_e32 v108, 16, v141
	v_and_b32_e32 v109, 0xffff0000, v141
	v_pk_mul_f32 v[112:113], v[104:105], v[112:113] op_sel_hi:[0,1]
	v_pk_mul_f32 v[110:111], v[104:105], v[110:111] op_sel_hi:[0,1]
	v_cmp_gt_f32_e32 vcc, s7, v102
	s_waitcnt vmcnt(1)
	v_pk_fma_f32 v[98:99], v[110:111], v[174:175], v[106:107]
	v_pk_fma_f32 v[100:101], v[112:113], v[176:177], v[108:109]
	global_store_dwordx4 v[166:167], v[98:101], off offset:16
	v_lshlrev_b32_e32 v110, 16, v162
	v_and_b32_e32 v111, 0xffff0000, v162
	v_lshlrev_b32_e32 v112, 16, v163
	v_and_b32_e32 v113, 0xffff0000, v163
	v_lshlrev_b32_e32 v106, 16, v158
	v_and_b32_e32 v107, 0xffff0000, v158
	v_lshlrev_b32_e32 v108, 16, v159
	v_and_b32_e32 v109, 0xffff0000, v159
	v_pk_mul_f32 v[112:113], v[104:105], v[112:113] op_sel_hi:[0,1]
	v_pk_mul_f32 v[110:111], v[104:105], v[110:111] op_sel_hi:[0,1]
	s_waitcnt vmcnt(2)
	v_pk_fma_f32 v[98:99], v[110:111], v[178:179], v[106:107]
	v_pk_fma_f32 v[100:101], v[112:113], v[180:181], v[108:109]
	global_store_dwordx4 v[166:167], v[98:101], off offset:2048
	v_lshlrev_b32_e32 v110, 16, v164
	v_and_b32_e32 v111, 0xffff0000, v164
	v_lshlrev_b32_e32 v112, 16, v165
	v_and_b32_e32 v113, 0xffff0000, v165
	v_lshlrev_b32_e32 v106, 16, v160
	v_and_b32_e32 v107, 0xffff0000, v160
	v_lshlrev_b32_e32 v108, 16, v161
	v_and_b32_e32 v109, 0xffff0000, v161
	v_pk_mul_f32 v[112:113], v[104:105], v[112:113] op_sel_hi:[0,1]
	v_pk_mul_f32 v[104:105], v[104:105], v[110:111] op_sel_hi:[0,1]
	v_lshlrev_b32_e32 v110, 16, v74
	v_and_b32_e32 v111, 0xffff0000, v74
	v_lshlrev_b32_e32 v74, 16, v75
	v_and_b32_e32 v75, 0xffff0000, v75
	s_waitcnt vmcnt(3)
	v_pk_fma_f32 v[98:99], v[104:105], v[182:183], v[106:107]
	v_pk_fma_f32 v[100:101], v[112:113], v[184:185], v[108:109]
	global_store_dwordx4 v[166:167], v[98:101], off offset:2064
	v_lshlrev_b64 v[104:105], 12, v[86:87]
	v_mul_f32_e32 v87, 0x4b800000, v102
	v_cndmask_b32_e32 v87, v102, v87, vcc
	v_rsq_f32_e32 v87, v87
	v_lshlrev_b32_e32 v106, 16, v118
	v_and_b32_e32 v107, 0xffff0000, v118
	v_lshlrev_b32_e32 v108, 16, v119
	v_mul_f32_e32 v97, 0x45800000, v87
	v_cndmask_b32_e32 v102, v87, v97, vcc
	v_and_b32_e32 v109, 0xffff0000, v119
	v_pk_mul_f32 v[74:75], v[102:103], v[74:75] op_sel_hi:[0,1]
	v_pk_mul_f32 v[110:111], v[102:103], v[110:111] op_sel_hi:[0,1]
	v_lshl_add_u64 v[104:105], v[84:85], 0, v[104:105]
	v_add_u32_e32 v86, s34, v86
	s_waitcnt vmcnt(4)
	v_pk_fma_f32 v[98:99], v[110:111], v[170:171], v[106:107]
	v_pk_fma_f32 v[100:101], v[74:75], v[172:173], v[108:109]
	global_store_dwordx4 v[104:105], v[98:101], off
	v_lshlrev_b32_e32 v108, 16, v76
	v_and_b32_e32 v109, 0xffff0000, v76
	v_lshlrev_b32_e32 v76, 16, v77
	v_and_b32_e32 v77, 0xffff0000, v77
	v_lshlrev_b32_e32 v74, 16, v120
	v_and_b32_e32 v75, 0xffff0000, v120
	v_lshlrev_b32_e32 v106, 16, v121
	v_and_b32_e32 v107, 0xffff0000, v121
	v_pk_mul_f32 v[76:77], v[102:103], v[76:77] op_sel_hi:[0,1]
	v_pk_mul_f32 v[108:109], v[102:103], v[108:109] op_sel_hi:[0,1]
	s_waitcnt vmcnt(5)
	v_pk_fma_f32 v[74:75], v[108:109], v[174:175], v[74:75]
	v_pk_fma_f32 v[76:77], v[76:77], v[176:177], v[106:107]
	global_store_dwordx4 v[104:105], v[74:77], off offset:16
	v_lshlrev_b32_e32 v100, 16, v66
	v_and_b32_e32 v101, 0xffff0000, v66
	v_lshlrev_b32_e32 v66, 16, v67
	v_and_b32_e32 v67, 0xffff0000, v67
	v_lshlrev_b32_e32 v98, 16, v70
	v_and_b32_e32 v99, 0xffff0000, v70
	v_lshlrev_b32_e32 v70, 16, v71
	v_and_b32_e32 v71, 0xffff0000, v71
	v_pk_mul_f32 v[66:67], v[102:103], v[66:67] op_sel_hi:[0,1]
	v_pk_mul_f32 v[100:101], v[102:103], v[100:101] op_sel_hi:[0,1]
	s_waitcnt vmcnt(6)
	v_pk_fma_f32 v[74:75], v[100:101], v[178:179], v[98:99]
	v_pk_fma_f32 v[76:77], v[66:67], v[180:181], v[70:71]
	global_store_dwordx4 v[104:105], v[74:77], off offset:2048
	v_lshlrev_b32_e32 v66, 16, v72
	v_and_b32_e32 v67, 0xffff0000, v72
	v_lshlrev_b32_e32 v70, 16, v73
	v_and_b32_e32 v71, 0xffff0000, v73
	v_lshlrev_b32_e32 v72, 16, v68
	v_and_b32_e32 v73, 0xffff0000, v68
	v_lshlrev_b32_e32 v68, 16, v69
	v_and_b32_e32 v69, 0xffff0000, v69
	v_pk_mul_f32 v[68:69], v[102:103], v[68:69] op_sel_hi:[0,1]
	v_pk_mul_f32 v[72:73], v[102:103], v[72:73] op_sel_hi:[0,1]
	s_waitcnt vmcnt(7)
	v_pk_fma_f32 v[66:67], v[72:73], v[182:183], v[66:67]
	v_pk_fma_f32 v[68:69], v[68:69], v[184:185], v[70:71]
	global_store_dwordx4 v[104:105], v[66:69], off offset:2064
	v_mov_b32_e32 v72, v62
	v_mov_b32_e32 v73, v38
	v_mov_b32_e32 v38, v63
	v_mov_b32_e32 v62, v64
	v_mov_b32_e32 v63, v40
	v_mov_b32_e32 v40, v65
	v_mov_b32_e32 v64, v58
	v_mov_b32_e32 v65, v34
	v_mov_b32_e32 v34, v59
	v_mov_b32_e32 v76, v54
	v_mov_b32_e32 v77, v46
	v_mov_b32_e32 v46, v55
	v_mov_b32_e32 v58, v60
	v_mov_b32_e32 v59, v36
	v_mov_b32_e32 v54, v56
	v_mov_b32_e32 v55, v48
	v_mov_b32_e32 v48, v57
	v_mov_b32_e32 v56, v50
	v_mov_b32_e32 v57, v42
	v_mov_b32_e32 v42, v51
	v_pk_add_f32 v[38:39], v[72:73], v[38:39]
	v_pk_add_f32 v[34:35], v[64:65], v[34:35]
	v_pk_add_f32 v[46:47], v[76:77], v[46:47]
	v_mov_b32_e32 v36, v61
	v_mov_b32_e32 v50, v52
	v_mov_b32_e32 v51, v44
	v_pk_add_f32 v[42:43], v[56:57], v[42:43]
	v_pk_add_f32 v[38:39], v[62:63], v[38:39]
	v_pk_add_f32 v[34:35], v[58:59], v[34:35]
	v_pk_add_f32 v[46:47], v[54:55], v[46:47]
	v_mov_b32_e32 v44, v53
	v_pk_add_f32 v[42:43], v[50:51], v[42:43]
	v_pk_add_f32 v[38:39], v[40:41], v[38:39]
	v_pk_add_f32 v[34:35], v[36:37], v[34:35]
	v_pk_add_f32 v[36:37], v[48:49], v[46:47]
	v_pk_add_f32 v[40:41], v[44:45], v[42:43]
	v_mov_b32_e32 v42, v36
	v_mov_b32_e32 v43, v38
	v_mov_b32_e32 v38, v37
	v_mov_b32_e32 v36, v40
	v_mov_b32_e32 v37, v34
	v_pk_add_f32 v[38:39], v[42:43], v[38:39]
	v_mov_b32_e32 v34, v41
	v_pk_add_f32 v[36:37], v[38:39], v[36:37]
	v_lshlrev_b32_e32 v74, 16, v26
	v_pk_add_f32 v[34:35], v[36:37], v[34:35]
	v_and_b32_e32 v75, 0xffff0000, v26
	v_pk_fma_f32 v[38:39], v[34:35], s[8:9], v[92:93] op_sel_hi:[1,0,0]
	v_lshlrev_b32_e32 v26, 16, v27
	v_mul_f32_e32 v34, 0x4b800000, v39
	v_cmp_gt_f32_e32 vcc, s7, v39
	v_and_b32_e32 v27, 0xffff0000, v27
	v_lshlrev_b64 v[70:71], 12, v[90:91]
	v_cndmask_b32_e32 v34, v39, v34, vcc
	v_rsq_f32_e32 v34, v34
	v_lshlrev_b32_e32 v60, 16, v30
	v_and_b32_e32 v61, 0xffff0000, v30
	v_lshlrev_b32_e32 v30, 16, v31
	v_mul_f32_e32 v35, 0x45800000, v34
	v_cndmask_b32_e32 v40, v34, v35, vcc
	v_and_b32_e32 v31, 0xffff0000, v31
	v_pk_mul_f32 v[26:27], v[40:41], v[26:27] op_sel_hi:[0,1]
	v_pk_mul_f32 v[34:35], v[40:41], v[74:75] op_sel_hi:[0,1]
	v_lshl_add_u64 v[70:71], v[84:85], 0, v[70:71]
	v_cmp_gt_f32_e32 vcc, s7, v38
	s_waitcnt vmcnt(8)
	v_pk_fma_f32 v[34:35], v[34:35], v[170:171], v[60:61]
	v_pk_fma_f32 v[36:37], v[26:27], v[172:173], v[30:31]
	global_store_dwordx4 v[70:71], v[34:37], off
	v_lshlrev_b32_e32 v26, 16, v32
	v_and_b32_e32 v27, 0xffff0000, v32
	v_lshlrev_b32_e32 v30, 16, v33
	v_and_b32_e32 v31, 0xffff0000, v33
	v_lshlrev_b32_e32 v32, 16, v28
	v_and_b32_e32 v33, 0xffff0000, v28
	v_lshlrev_b32_e32 v28, 16, v29
	v_and_b32_e32 v29, 0xffff0000, v29
	v_pk_mul_f32 v[28:29], v[40:41], v[28:29] op_sel_hi:[0,1]
	v_pk_mul_f32 v[32:33], v[40:41], v[32:33] op_sel_hi:[0,1]
	s_waitcnt vmcnt(9)
	v_pk_fma_f32 v[26:27], v[32:33], v[174:175], v[26:27]
	v_pk_fma_f32 v[28:29], v[28:29], v[176:177], v[30:31]
	global_store_dwordx4 v[70:71], v[26:29], off offset:16
	v_lshlrev_b32_e32 v32, 16, v18
	v_and_b32_e32 v33, 0xffff0000, v18
	v_lshlrev_b32_e32 v18, 16, v19
	v_and_b32_e32 v19, 0xffff0000, v19
	v_lshlrev_b32_e32 v30, 16, v22
	v_and_b32_e32 v31, 0xffff0000, v22
	v_lshlrev_b32_e32 v22, 16, v23
	v_and_b32_e32 v23, 0xffff0000, v23
	v_pk_mul_f32 v[18:19], v[40:41], v[18:19] op_sel_hi:[0,1]
	v_pk_mul_f32 v[32:33], v[40:41], v[32:33] op_sel_hi:[0,1]
	s_waitcnt vmcnt(10)
	v_pk_fma_f32 v[26:27], v[32:33], v[178:179], v[30:31]
	v_pk_fma_f32 v[28:29], v[18:19], v[180:181], v[22:23]
	global_store_dwordx4 v[70:71], v[26:29], off offset:2048
	v_lshlrev_b32_e32 v18, 16, v24
	v_and_b32_e32 v19, 0xffff0000, v24
	v_lshlrev_b32_e32 v22, 16, v25
	v_and_b32_e32 v23, 0xffff0000, v25
	v_lshlrev_b32_e32 v24, 16, v20
	v_and_b32_e32 v25, 0xffff0000, v20
	v_lshlrev_b32_e32 v20, 16, v21
	v_and_b32_e32 v21, 0xffff0000, v21
	v_pk_mul_f32 v[20:21], v[40:41], v[20:21] op_sel_hi:[0,1]
	v_pk_mul_f32 v[24:25], v[40:41], v[24:25] op_sel_hi:[0,1]
	s_waitcnt vmcnt(11)
	v_pk_fma_f32 v[18:19], v[24:25], v[182:183], v[18:19]
	v_pk_fma_f32 v[20:21], v[20:21], v[184:185], v[22:23]
	global_store_dwordx4 v[70:71], v[18:21], off offset:2064
	v_mul_f32_e32 v28, 0x4b800000, v38
	v_cndmask_b32_e32 v28, v38, v28, vcc
	v_rsq_f32_e32 v28, v28
	v_lshlrev_b32_e32 v24, 16, v14
	v_and_b32_e32 v25, 0xffff0000, v14
	v_lshlrev_b32_e32 v14, 16, v15
	v_mul_f32_e32 v29, 0x45800000, v28
	v_and_b32_e32 v15, 0xffff0000, v15
	v_cndmask_b32_e32 v28, v28, v29, vcc
	v_lshlrev_b64 v[22:23], 12, v[88:89]
	v_lshlrev_b32_e32 v26, 16, v10
	v_and_b32_e32 v27, 0xffff0000, v10
	v_lshlrev_b32_e32 v10, 16, v11
	v_and_b32_e32 v11, 0xffff0000, v11
	v_pk_mul_f32 v[14:15], v[28:29], v[14:15] op_sel_hi:[0,1]
	v_pk_mul_f32 v[24:25], v[28:29], v[24:25] op_sel_hi:[0,1]
	v_lshl_add_u64 v[22:23], v[84:85], 0, v[22:23]
	v_cmp_le_i32_e32 vcc, s25, v0
	s_or_b64 s[4:5], vcc, s[4:5]
	s_waitcnt vmcnt(12)
	v_pk_fma_f32 v[18:19], v[24:25], v[170:171], v[26:27]
	v_pk_fma_f32 v[20:21], v[14:15], v[172:173], v[10:11]
	global_store_dwordx4 v[22:23], v[18:21], off
	v_lshlrev_b32_e32 v10, 16, v16
	v_and_b32_e32 v11, 0xffff0000, v16
	v_lshlrev_b32_e32 v14, 16, v17
	v_and_b32_e32 v15, 0xffff0000, v17
	v_lshlrev_b32_e32 v16, 16, v12
	v_and_b32_e32 v17, 0xffff0000, v12
	v_lshlrev_b32_e32 v12, 16, v13
	v_and_b32_e32 v13, 0xffff0000, v13
	v_pk_mul_f32 v[14:15], v[28:29], v[14:15] op_sel_hi:[0,1]
	v_pk_mul_f32 v[10:11], v[28:29], v[10:11] op_sel_hi:[0,1]
	s_waitcnt vmcnt(13)
	v_pk_fma_f32 v[10:11], v[10:11], v[174:175], v[16:17]
	v_pk_fma_f32 v[12:13], v[14:15], v[176:177], v[12:13]
	global_store_dwordx4 v[22:23], v[10:13], off offset:16
	v_lshlrev_b32_e32 v14, 16, v6
	v_and_b32_e32 v15, 0xffff0000, v6
	v_lshlrev_b32_e32 v6, 16, v7
	v_and_b32_e32 v7, 0xffff0000, v7
	v_lshlrev_b32_e32 v16, 16, v2
	v_and_b32_e32 v17, 0xffff0000, v2
	v_lshlrev_b32_e32 v2, 16, v3
	v_and_b32_e32 v3, 0xffff0000, v3
	v_pk_mul_f32 v[6:7], v[28:29], v[6:7] op_sel_hi:[0,1]
	v_pk_mul_f32 v[14:15], v[28:29], v[14:15] op_sel_hi:[0,1]
	s_waitcnt vmcnt(14)
	v_pk_fma_f32 v[10:11], v[14:15], v[178:179], v[16:17]
	v_pk_fma_f32 v[12:13], v[6:7], v[180:181], v[2:3]
	global_store_dwordx4 v[22:23], v[10:13], off offset:2048
	v_lshlrev_b32_e32 v2, 16, v8
	v_and_b32_e32 v3, 0xffff0000, v8
	v_lshlrev_b32_e32 v6, 16, v9
	v_and_b32_e32 v7, 0xffff0000, v9
	v_lshlrev_b32_e32 v8, 16, v4
	v_and_b32_e32 v9, 0xffff0000, v4
	v_lshlrev_b32_e32 v4, 16, v5
	v_and_b32_e32 v5, 0xffff0000, v5
	v_pk_mul_f32 v[6:7], v[28:29], v[6:7] op_sel_hi:[0,1]
	v_pk_mul_f32 v[2:3], v[28:29], v[2:3] op_sel_hi:[0,1]
	s_waitcnt vmcnt(15)
	v_pk_fma_f32 v[2:3], v[2:3], v[182:183], v[8:9]
	v_pk_fma_f32 v[4:5], v[6:7], v[184:185], v[4:5]
	global_store_dwordx4 v[22:23], v[2:5], off offset:2064
	s_andn2_b64 exec, exec, s[4:5]
	s_cbranch_execnz .LBB0_524

.LBB0_951:
	s_or_b64 exec, exec, s[4:5]
	v_readlane_b32 s0, v252, 62
	s_sub_i32 s0, s0, s2
	s_ashr_i32 s1, s0, 31
	s_abs_i32 s0, s0
	v_readlane_b32 s3, v251, 5
	s_mul_hi_u32 s3, s0, s3
	v_readlane_b32 s6, v251, 4
	s_mul_i32 s4, s3, s6
	s_sub_i32 s0, s0, s4
	s_xor_b32 s1, s1, s33
	s_add_i32 s4, s3, 1
	s_sub_i32 s5, s0, s6
	s_cmp_ge_u32 s0, s6
	s_cselect_b32 s3, s4, s3
	s_cselect_b32 s0, s5, s0
	s_add_i32 s4, s3, 1
	s_cmp_ge_u32 s0, s6
	v_ashrrev_i32_e32 v3, 6, v2
	s_cselect_b32 s0, s4, s3
	v_mul_lo_u32 v0, v3, s90
	s_xor_b32 s0, s0, s1
	v_add_u32_e32 v93, s2, v0
	s_sub_i32 s0, s0, s1
	v_readlane_b32 s1, v252, 63
	v_and_b32_e32 v106, 63, v2
	v_lshlrev_b32_e32 v90, 5, v106
	v_sub_u32_e32 v0, s1, v93
	v_sub_u32_e32 v5, 0, v0
	v_ashrrev_i32_e32 v4, 31, v0
	v_readlane_b32 s1, v251, 8
	v_max_i32_e32 v0, v0, v5
	v_mul_hi_u32 v5, v0, v194
	v_xor_b32_e32 v4, s1, v4
	v_readlane_b32 s1, v251, 6
	s_nop 1
	v_mul_lo_u32 v6, v5, s1
	v_sub_u32_e32 v0, v0, v6
	v_add_u32_e32 v6, 1, v5
	v_cmp_le_u32_e32 vcc, s1, v0
	s_nop 1
	v_cndmask_b32_e32 v5, v5, v6, vcc
	v_subrev_u32_e32 v6, s1, v0
	v_cndmask_b32_e32 v0, v0, v6, vcc
	v_add_u32_e32 v6, 1, v5
	v_cmp_le_u32_e32 vcc, s1, v0
	s_nop 1
	v_cndmask_b32_e32 v0, v5, v6, vcc
	v_xor_b32_e32 v0, v0, v4
	v_sub_u32_e32 v0, v0, v4
	v_max_i32_e32 v107, s0, v0
	v_cmp_lt_i32_e32 vcc, 0, v107
	s_and_saveexec_b64 s[0:1], vcc
	s_cbranch_execz .LBB0_1038
	v_readlane_b32 s4, v251, 36
	v_lshlrev_b32_e32 v0, 3, v2
	v_mov_b32_e32 v91, v1
	v_readlane_b32 s5, v251, 37
	v_readlane_b32 s6, v251, 38
	v_readlane_b32 s7, v251, 39
	v_readlane_b32 s8, v251, 40
	v_readlane_b32 s9, v251, 41
	v_readlane_b32 s10, v251, 42
	v_readlane_b32 s11, v251, 43
	v_readlane_b32 s12, v251, 44
	v_readlane_b32 s13, v251, 45
	v_readlane_b32 s14, v251, 46
	v_readlane_b32 s15, v251, 47
	v_readlane_b32 s16, v251, 48
	v_readlane_b32 s17, v251, 49
	v_readlane_b32 s18, v251, 50
	v_readlane_b32 s19, v251, 51
	v_ashrrev_i32_e32 v108, 3, v2
	v_and_b32_e32 v92, 56, v0
	s_movk_i32 s3, 0x104
	v_lshl_add_u64 v[94:95], s[4:5], 0, v[90:91]
	global_load_dwordx4 v[160:163], v[94:95], off
	global_load_dwordx4 v[164:167], v[94:95], off offset:16
	global_load_dwordx4 v[168:171], v[94:95], off offset:2048
	global_load_dwordx4 v[172:175], v[94:95], off offset:2064
	v_readlane_b32 s4, v250, 7
	v_and_b32_e32 v109, 24, v0
	v_mul_lo_u32 v0, v108, s3
	v_lshlrev_b32_e32 v2, 2, v92
	s_movk_i32 s3, 0x100
	v_readlane_b32 s5, v250, 8
	v_add3_u32 v110, s3, v0, v2
	v_lshl_add_u32 v4, v108, 2, v201
	v_mul_u32_u24_e32 v5, 0x104, v92
	v_readlane_b32 s8, v250, 11
	v_readlane_b32 s9, v250, 12
	v_readlane_b32 s10, v250, 13
	v_lshl_add_u64 v[96:97], s[4:5], 0, v[90:91]
	v_lshlrev_b32_e32 v0, 4, v106
	v_readlane_b32 s4, v251, 21
	v_mov_b32_e32 v2, 0
	v_lshl_add_u64 v[98:99], s[86:87], 0, v[0:1]
	s_lshl_b32 s3, s2, 2
	v_mul_lo_u32 v91, s4, v3
	s_mov_b32 s8, 0
	s_mov_b64 s[4:5], 0
	v_add_u32_e32 v111, v4, v5
	s_mov_b32 s9, s2
	s_waitcnt vmcnt(0)
	v_mov_b32_e32 v112, v93
	s_mov_b32 s10, 0
	v_mov_b32_e32 v3, v2
	v_mov_b32_e32 v4, v2
	v_mov_b32_e32 v5, v2
	v_mov_b32_e32 v14, v2
	v_mov_b32_e32 v15, v2
	v_mov_b32_e32 v16, v2
	v_mov_b32_e32 v17, v2
	v_mov_b32_e32 v22, v2
	v_mov_b32_e32 v23, v2
	v_mov_b32_e32 v24, v2
	v_mov_b32_e32 v25, v2
	v_mov_b32_e32 v30, v2
	v_mov_b32_e32 v31, v2
	v_mov_b32_e32 v32, v2
	v_mov_b32_e32 v33, v2
	v_readlane_b32 s6, v250, 9
	v_readlane_b32 s7, v250, 10
	v_readlane_b32 s11, v250, 14
	v_readlane_b32 s12, v250, 15
	v_readlane_b32 s13, v250, 16
	v_readlane_b32 s14, v250, 17
	v_readlane_b32 s15, v250, 18
	v_readlane_b32 s16, v250, 19
	v_readlane_b32 s17, v250, 20
	v_readlane_b32 s18, v250, 21
	v_readlane_b32 s19, v250, 22
	s_branch .LBB0_956

.LBB0_962:
	v_add_u32_e32 v34, s3, v91
	v_ashrrev_i32_e32 v35, 31, v34
	v_lshlrev_b64 v[36:37], 12, v[34:35]
	v_lshl_add_u64 v[36:37], v[96:97], 0, v[36:37]
	global_load_dwordx4 v[78:81], v[36:37], off
	global_load_dwordx4 v[74:77], v[36:37], off offset:16
	global_load_dwordx4 v[70:73], v[36:37], off offset:2048
	global_load_dwordx4 v[66:69], v[36:37], off offset:2064
	v_and_b32_e32 v0, 64, v199
	v_xor_b32_e32 v36, 32, v199
	v_add_u32_e32 v55, 64, v0
	v_xor_b32_e32 v37, 16, v199
	v_cmp_lt_i32_e32 vcc, v36, v55
	v_xor_b32_e32 v38, 8, v199
	v_xor_b32_e32 v52, 4, v199
	v_cndmask_b32_e32 v0, v199, v36, vcc
	v_cmp_lt_i32_e32 vcc, v37, v55
	v_lshlrev_b32_e32 v0, 2, v0
	v_xor_b32_e32 v53, 2, v199
	v_cndmask_b32_e32 v56, v199, v37, vcc
	v_cmp_lt_i32_e32 vcc, v38, v55
	v_lshlrev_b32_e32 v113, 2, v56
	v_add_u32_e32 v104, 1, v34
	v_cndmask_b32_e32 v57, v199, v38, vcc
	v_lshlrev_b32_e32 v114, 2, v57
	v_cmp_lt_i32_e32 vcc, v52, v55
	v_add_u32_e32 v102, 2, v34
	v_ashrrev_i32_e32 v105, 31, v104
	v_ashrrev_i32_e32 v103, 31, v102
	v_add_u32_e32 v100, 3, v34
	v_lshlrev_b64 v[34:35], 11, v[34:35]
	v_lshl_add_u64 v[134:135], v[98:99], 0, v[34:35]
	v_xor_b32_e32 v54, 1, v199
	s_mov_b32 s12, 0x800000
	v_ashrrev_i32_e32 v101, 31, v100
	s_waitcnt vmcnt(3)
	v_mov_b32_e32 v38, v79
	s_waitcnt vmcnt(2)
	v_mov_b32_e32 v39, v75
	v_mov_b32_e32 v36, v78
	v_mov_b32_e32 v37, v74
	s_waitcnt vmcnt(1)
	v_mov_b32_e32 v46, v71
	s_waitcnt vmcnt(0)
	v_mov_b32_e32 v47, v67
	v_pk_mul_f32 v[38:39], v[38:39], v[38:39]
	v_mov_b32_e32 v40, v80
	v_mov_b32_e32 v41, v76
	v_mov_b32_e32 v44, v70
	v_mov_b32_e32 v45, v66
	v_pk_mul_f32 v[46:47], v[46:47], v[46:47]
	v_pk_fma_f32 v[36:37], v[36:37], v[36:37], v[38:39]
	v_mov_b32_e32 v42, v81
	v_mov_b32_e32 v43, v77
	v_mov_b32_e32 v48, v72
	v_mov_b32_e32 v49, v68
	v_pk_fma_f32 v[38:39], v[44:45], v[44:45], v[46:47]
	v_pk_fma_f32 v[36:37], v[40:41], v[40:41], v[36:37]
	v_mov_b32_e32 v50, v73
	v_mov_b32_e32 v51, v69
	v_pk_fma_f32 v[38:39], v[48:49], v[48:49], v[38:39]
	v_pk_fma_f32 v[36:37], v[42:43], v[42:43], v[36:37]
	v_pk_fma_f32 v[38:39], v[50:51], v[50:51], v[38:39]
	v_add_f32_e32 v36, v36, v37
	v_add_f32_e32 v36, v36, v38
	v_add_f32_e32 v36, v36, v39
	ds_bpermute_b32 v37, v0, v36
	v_cndmask_b32_e32 v42, v199, v52, vcc
	v_cmp_lt_i32_e32 vcc, v53, v55
	v_lshlrev_b32_e32 v116, 2, v42
	v_lshlrev_b64 v[38:39], 12, v[102:103]
	s_waitcnt lgkmcnt(0)
	v_add_f32_e32 v40, v36, v37
	ds_bpermute_b32 v41, v113, v40
	v_cndmask_b32_e32 v43, v199, v53, vcc
	v_lshlrev_b32_e32 v115, 2, v43
	v_lshlrev_b64 v[36:37], 12, v[104:105]
	v_lshl_add_u64 v[34:35], v[96:97], 0, v[36:37]
	s_waitcnt lgkmcnt(0)
	v_add_f32_e32 v45, v40, v41
	ds_bpermute_b32 v46, v114, v45
	v_lshl_add_u64 v[36:37], v[96:97], 0, v[38:39]
	v_cmp_lt_i32_e32 vcc, v54, v55
	global_load_dwordx4 v[126:129], v[34:35], off
	global_load_dwordx4 v[130:133], v[34:35], off offset:16
	global_load_dwordx4 v[86:89], v[34:35], off offset:2048
	global_load_dwordx4 v[82:85], v[34:35], off offset:2064
	v_cndmask_b32_e32 v44, v199, v54, vcc
	s_waitcnt lgkmcnt(0)
	v_add_f32_e32 v42, v45, v46
	ds_bpermute_b32 v43, v116, v42
	v_lshlrev_b32_e32 v117, 2, v44
	v_lshlrev_b64 v[40:41], 12, v[100:101]
	v_lshl_add_u64 v[136:137], v[96:97], 0, v[40:41]
	global_load_dwordx4 v[62:65], v[36:37], off
	global_load_dwordx4 v[58:61], v[36:37], off offset:16
	global_load_dwordx4 v[54:57], v[36:37], off offset:2048
	global_load_dwordx4 v[50:53], v[36:37], off offset:2064
	s_waitcnt lgkmcnt(0)
	v_add_f32_e32 v38, v42, v43
	ds_bpermute_b32 v39, v115, v38
	s_waitcnt lgkmcnt(0)
	v_add_f32_e32 v34, v38, v39
	ds_bpermute_b32 v35, v117, v34
	s_waitcnt lgkmcnt(0)
	v_add_f32_e32 v34, v34, v35
	v_fmamk_f32 v34, v34, 0x3a800000, v198
	v_mul_f32_e32 v35, 0x4b800000, v34
	v_cmp_gt_f32_e32 vcc, s12, v34
	s_nop 1
	v_cndmask_b32_e32 v34, v34, v35, vcc
	v_rsq_f32_e32 v138, v34
	global_load_dwordx4 v[46:49], v[136:137], off
	global_load_dwordx4 v[42:45], v[136:137], off offset:16
	global_load_dwordx4 v[38:41], v[136:137], off offset:2048
	global_load_dwordx4 v[34:37], v[136:137], off offset:2064
	v_mul_f32_e32 v136, 0x45800000, v138
	v_cndmask_b32_e32 v136, v138, v136, vcc
	v_pk_mul_f32 v[74:75], v[74:75], v[136:137] op_sel_hi:[1,0]
	v_pk_mul_f32 v[76:77], v[76:77], v[136:137] op_sel_hi:[1,0]
	v_pk_mul_f32 v[78:79], v[78:79], v[136:137] op_sel_hi:[1,0]
	v_pk_mul_f32 v[80:81], v[80:81], v[136:137] op_sel_hi:[1,0]
	s_waitcnt vmcnt(12)
	v_pk_mul_f32 v[120:121], v[166:167], v[76:77]
	v_pk_mul_f32 v[76:77], v[164:165], v[74:75]
	s_waitcnt vmcnt(12)
	v_pk_mul_f32 v[80:81], v[162:163], v[80:81]
	v_pk_mul_f32 v[78:79], v[160:161], v[78:79]
	v_pk_mul_f32 v[70:71], v[70:71], v[136:137] op_sel_hi:[1,0]
	v_cvt_pk_bf16_f32 v74, v78, v79
	v_cvt_pk_bf16_f32 v75, v80, v81
	v_cvt_pk_bf16_f32 v76, v76, v77
	v_cvt_pk_bf16_f32 v77, v120, v121
	global_store_dwordx4 v[134:135], v[74:77], off
	s_nop 0
	v_pk_mul_f32 v[66:67], v[66:67], v[136:137] op_sel_hi:[1,0]
	v_pk_mul_f32 v[68:69], v[68:69], v[136:137] op_sel_hi:[1,0]
	v_pk_mul_f32 v[72:73], v[72:73], v[136:137] op_sel_hi:[1,0]
	s_waitcnt vmcnt(12)
	v_mov_b32_e32 v118, v128
	s_waitcnt vmcnt(11)
	v_mov_b32_e32 v119, v132
	s_waitcnt vmcnt(10)
	v_mov_b32_e32 v120, v88
	s_waitcnt vmcnt(9)
	v_mov_b32_e32 v121, v84
	v_mov_b32_e32 v122, v129
	v_mov_b32_e32 v123, v133
	v_mov_b32_e32 v124, v89
	v_mov_b32_e32 v125, v85
	s_waitcnt vmcnt(1)
	v_pk_mul_f32 v[70:71], v[168:169], v[70:71]
	s_waitcnt vmcnt(1)
	v_pk_mul_f32 v[74:75], v[174:175], v[68:69]
	v_pk_mul_f32 v[68:69], v[172:173], v[66:67]
	v_pk_mul_f32 v[72:73], v[170:171], v[72:73]
	v_cvt_pk_bf16_f32 v66, v70, v71
	v_mov_b32_e32 v76, v127
	v_cvt_pk_bf16_f32 v67, v72, v73
	v_cvt_pk_bf16_f32 v68, v68, v69
	v_cvt_pk_bf16_f32 v69, v74, v75
	global_store_dwordx4 v[134:135], v[66:69], off offset:1024
	s_nop 0
	v_mov_b32_e32 v77, v131
	v_mov_b32_e32 v74, v126
	v_mov_b32_e32 v75, v130
	v_mov_b32_e32 v80, v87
	v_mov_b32_e32 v81, v83
	v_pk_mul_f32 v[76:77], v[76:77], v[76:77]
	v_mov_b32_e32 v78, v86
	v_mov_b32_e32 v79, v82
	v_pk_mul_f32 v[80:81], v[80:81], v[80:81]
	v_pk_fma_f32 v[74:75], v[74:75], v[74:75], v[76:77]
	v_pk_fma_f32 v[76:77], v[78:79], v[78:79], v[80:81]
	v_pk_fma_f32 v[74:75], v[118:119], v[118:119], v[74:75]
	v_pk_fma_f32 v[76:77], v[120:121], v[120:121], v[76:77]
	v_pk_fma_f32 v[74:75], v[122:123], v[122:123], v[74:75]
	v_pk_fma_f32 v[76:77], v[124:125], v[124:125], v[76:77]
	v_add_f32_e32 v74, v74, v75
	v_add_f32_e32 v74, v74, v76
	v_add_f32_e32 v74, v74, v77
	ds_bpermute_b32 v75, v0, v74
	s_waitcnt lgkmcnt(0)
	v_add_f32_e32 v74, v74, v75
	ds_bpermute_b32 v75, v113, v74
	s_waitcnt lgkmcnt(0)
	v_add_f32_e32 v74, v74, v75
	ds_bpermute_b32 v75, v114, v74
	s_waitcnt lgkmcnt(0)
	v_add_f32_e32 v74, v74, v75
	ds_bpermute_b32 v75, v116, v74
	s_waitcnt lgkmcnt(0)
	v_add_f32_e32 v74, v74, v75
	ds_bpermute_b32 v75, v115, v74
	s_waitcnt lgkmcnt(0)
	v_add_f32_e32 v74, v74, v75
	ds_bpermute_b32 v75, v117, v74
	s_waitcnt lgkmcnt(0)
	v_add_f32_e32 v74, v74, v75
	v_fmamk_f32 v74, v74, 0x3a800000, v198
	v_mul_f32_e32 v75, 0x4b800000, v74
	v_cmp_gt_f32_e32 vcc, s12, v74
	s_nop 1
	v_cndmask_b32_e32 v74, v74, v75, vcc
	v_rsq_f32_e32 v76, v74
	v_lshlrev_b64 v[74:75], 11, v[104:105]
	v_lshl_add_u64 v[74:75], v[98:99], 0, v[74:75]
	v_mul_f32_e32 v77, 0x45800000, v76
	v_cndmask_b32_e32 v76, v76, v77, vcc
	v_pk_mul_f32 v[78:79], v[126:127], v[76:77] op_sel_hi:[1,0]
	v_pk_mul_f32 v[80:81], v[128:129], v[76:77] op_sel_hi:[1,0]
	v_pk_mul_f32 v[104:105], v[130:131], v[76:77] op_sel_hi:[1,0]
	v_pk_mul_f32 v[118:119], v[132:133], v[76:77] op_sel_hi:[1,0]
	v_pk_mul_f32 v[82:83], v[82:83], v[76:77] op_sel_hi:[1,0]
	s_waitcnt vmcnt(2)
	v_pk_mul_f32 v[68:69], v[162:163], v[80:81]
	v_pk_mul_f32 v[66:67], v[160:161], v[78:79]
	s_waitcnt vmcnt(2)
	v_pk_mul_f32 v[72:73], v[166:167], v[118:119]
	v_pk_mul_f32 v[70:71], v[164:165], v[104:105]
	v_cvt_pk_bf16_f32 v66, v66, v67
	v_cvt_pk_bf16_f32 v67, v68, v69
	v_pk_mul_f32 v[78:79], v[86:87], v[76:77] op_sel_hi:[1,0]
	v_cvt_pk_bf16_f32 v68, v70, v71
	v_cvt_pk_bf16_f32 v69, v72, v73
	global_store_dwordx4 v[74:75], v[66:69], off
	s_nop 0
	v_pk_mul_f32 v[80:81], v[88:89], v[76:77] op_sel_hi:[1,0]
	v_pk_mul_f32 v[76:77], v[84:85], v[76:77] op_sel_hi:[1,0]
	v_mov_b32_e32 v84, v65
	v_mov_b32_e32 v85, v61
	v_mov_b32_e32 v86, v56
	v_mov_b32_e32 v87, v52
	v_mov_b32_e32 v88, v57
	v_mov_b32_e32 v89, v53
	s_waitcnt vmcnt(3)
	v_pk_mul_f32 v[68:69], v[170:171], v[80:81]
	v_pk_mul_f32 v[66:67], v[168:169], v[78:79]
	s_waitcnt vmcnt(3)
	v_pk_mul_f32 v[72:73], v[174:175], v[76:77]
	v_pk_mul_f32 v[70:71], v[172:173], v[82:83]
	v_cvt_pk_bf16_f32 v66, v66, v67
	v_cvt_pk_bf16_f32 v67, v68, v69
	v_mov_b32_e32 v76, v63
	v_cvt_pk_bf16_f32 v68, v70, v71
	v_cvt_pk_bf16_f32 v69, v72, v73
	global_store_dwordx4 v[74:75], v[66:69], off offset:1024
	s_nop 0
	v_mov_b32_e32 v77, v59
	v_mov_b32_e32 v74, v62
	v_mov_b32_e32 v75, v58
	v_mov_b32_e32 v82, v55
	v_mov_b32_e32 v83, v51
	v_pk_mul_f32 v[76:77], v[76:77], v[76:77]
	v_mov_b32_e32 v78, v64
	v_mov_b32_e32 v79, v60
	v_mov_b32_e32 v80, v54
	v_mov_b32_e32 v81, v50
	v_pk_mul_f32 v[82:83], v[82:83], v[82:83]
	v_pk_fma_f32 v[74:75], v[74:75], v[74:75], v[76:77]
	v_pk_fma_f32 v[76:77], v[80:81], v[80:81], v[82:83]
	v_pk_fma_f32 v[74:75], v[78:79], v[78:79], v[74:75]
	v_pk_fma_f32 v[76:77], v[86:87], v[86:87], v[76:77]
	v_pk_fma_f32 v[74:75], v[84:85], v[84:85], v[74:75]
	v_pk_fma_f32 v[76:77], v[88:89], v[88:89], v[76:77]
	v_add_f32_e32 v74, v74, v75
	v_add_f32_e32 v74, v74, v76
	v_add_f32_e32 v74, v74, v77
	ds_bpermute_b32 v75, v0, v74
	s_waitcnt lgkmcnt(0)
	v_add_f32_e32 v74, v74, v75
	ds_bpermute_b32 v75, v113, v74
	s_waitcnt lgkmcnt(0)
	v_add_f32_e32 v74, v74, v75
	ds_bpermute_b32 v75, v114, v74
	s_waitcnt lgkmcnt(0)
	v_add_f32_e32 v74, v74, v75
	ds_bpermute_b32 v75, v116, v74
	s_waitcnt lgkmcnt(0)
	v_add_f32_e32 v74, v74, v75
	ds_bpermute_b32 v75, v115, v74
	s_waitcnt lgkmcnt(0)
	v_add_f32_e32 v74, v74, v75
	ds_bpermute_b32 v75, v117, v74
	s_waitcnt lgkmcnt(0)
	v_add_f32_e32 v74, v74, v75
	v_fmamk_f32 v74, v74, 0x3a800000, v198
	v_mul_f32_e32 v75, 0x4b800000, v74
	v_cmp_gt_f32_e32 vcc, s12, v74
	s_nop 1
	v_cndmask_b32_e32 v74, v74, v75, vcc
	v_rsq_f32_e32 v76, v74
	v_lshlrev_b64 v[74:75], 11, v[102:103]
	v_lshl_add_u64 v[74:75], v[98:99], 0, v[74:75]
	v_mul_f32_e32 v77, 0x45800000, v76
	v_cndmask_b32_e32 v76, v76, v77, vcc
	v_pk_mul_f32 v[62:63], v[62:63], v[76:77] op_sel_hi:[1,0]
	v_pk_mul_f32 v[58:59], v[58:59], v[76:77] op_sel_hi:[1,0]
	v_pk_mul_f32 v[60:61], v[60:61], v[76:77] op_sel_hi:[1,0]
	v_pk_mul_f32 v[64:65], v[64:65], v[76:77] op_sel_hi:[1,0]
	v_pk_mul_f32 v[54:55], v[54:55], v[76:77] op_sel_hi:[1,0]
	v_pk_mul_f32 v[50:51], v[50:51], v[76:77] op_sel_hi:[1,0]
	v_pk_mul_f32 v[52:53], v[52:53], v[76:77] op_sel_hi:[1,0]
	v_pk_mul_f32 v[56:57], v[56:57], v[76:77] op_sel_hi:[1,0]
	s_waitcnt vmcnt(4)
	v_pk_mul_f32 v[62:63], v[160:161], v[62:63]
	s_waitcnt vmcnt(4)
	v_pk_mul_f32 v[66:67], v[166:167], v[60:61]
	v_pk_mul_f32 v[60:61], v[164:165], v[58:59]
	v_pk_mul_f32 v[64:65], v[162:163], v[64:65]
	v_cvt_pk_bf16_f32 v58, v62, v63
	v_mov_b32_e32 v68, v39
	v_cvt_pk_bf16_f32 v59, v64, v65
	v_cvt_pk_bf16_f32 v60, v60, v61
	v_cvt_pk_bf16_f32 v61, v66, v67
	global_store_dwordx4 v[74:75], v[58:61], off
	s_nop 0
	v_mov_b32_e32 v69, v35
	v_mov_b32_e32 v66, v38
	v_mov_b32_e32 v67, v34
	v_pk_mul_f32 v[68:69], v[68:69], v[68:69]
	v_mov_b32_e32 v70, v40
	v_mov_b32_e32 v71, v36
	v_mov_b32_e32 v72, v41
	v_mov_b32_e32 v73, v37
	s_waitcnt vmcnt(5)
	v_pk_mul_f32 v[54:55], v[168:169], v[54:55]
	s_waitcnt vmcnt(5)
	v_pk_mul_f32 v[58:59], v[174:175], v[52:53]
	v_pk_mul_f32 v[52:53], v[172:173], v[50:51]
	v_pk_mul_f32 v[56:57], v[170:171], v[56:57]
	v_cvt_pk_bf16_f32 v50, v54, v55
	v_mov_b32_e32 v60, v47
	v_cvt_pk_bf16_f32 v51, v56, v57
	v_cvt_pk_bf16_f32 v52, v52, v53
	v_cvt_pk_bf16_f32 v53, v58, v59
	global_store_dwordx4 v[74:75], v[50:53], off offset:1024
	s_nop 0
	v_mov_b32_e32 v61, v43
	v_mov_b32_e32 v58, v46
	v_mov_b32_e32 v59, v42
	v_pk_mul_f32 v[60:61], v[60:61], v[60:61]
	v_mov_b32_e32 v62, v48
	v_mov_b32_e32 v63, v44
	v_pk_fma_f32 v[58:59], v[58:59], v[58:59], v[60:61]
	v_mov_b32_e32 v64, v49
	v_mov_b32_e32 v65, v45
	v_pk_fma_f32 v[60:61], v[66:67], v[66:67], v[68:69]
	v_pk_fma_f32 v[58:59], v[62:63], v[62:63], v[58:59]
	v_pk_fma_f32 v[60:61], v[70:71], v[70:71], v[60:61]
	v_pk_fma_f32 v[58:59], v[64:65], v[64:65], v[58:59]
	v_pk_fma_f32 v[60:61], v[72:73], v[72:73], v[60:61]
	v_add_f32_e32 v58, v58, v59
	v_add_f32_e32 v58, v58, v60
	v_add_f32_e32 v58, v58, v61
	ds_bpermute_b32 v0, v0, v58
	s_waitcnt lgkmcnt(0)
	v_add_f32_e32 v0, v58, v0
	ds_bpermute_b32 v58, v113, v0
	s_waitcnt lgkmcnt(0)
	v_add_f32_e32 v0, v0, v58
	ds_bpermute_b32 v58, v114, v0
	s_waitcnt lgkmcnt(0)
	v_add_f32_e32 v0, v0, v58
	ds_bpermute_b32 v58, v116, v0
	s_waitcnt lgkmcnt(0)
	v_add_f32_e32 v0, v0, v58
	ds_bpermute_b32 v58, v115, v0
	s_waitcnt lgkmcnt(0)
	v_add_f32_e32 v0, v0, v58
	ds_bpermute_b32 v58, v117, v0
	s_waitcnt lgkmcnt(0)
	v_add_f32_e32 v0, v0, v58
	v_fmamk_f32 v0, v0, 0x3a800000, v198
	v_mul_f32_e32 v58, 0x4b800000, v0
	v_cmp_gt_f32_e32 vcc, s12, v0
	s_nop 1
	v_cndmask_b32_e32 v0, v0, v58, vcc
	v_rsq_f32_e32 v0, v0
	v_lshlrev_b64 v[58:59], 11, v[100:101]
	v_lshl_add_u64 v[58:59], v[98:99], 0, v[58:59]
	v_mul_f32_e32 v60, 0x45800000, v0
	v_cndmask_b32_e32 v0, v0, v60, vcc
	v_pk_mul_f32 v[46:47], v[46:47], v[0:1] op_sel_hi:[1,0]
	v_pk_mul_f32 v[42:43], v[42:43], v[0:1] op_sel_hi:[1,0]
	v_pk_mul_f32 v[44:45], v[44:45], v[0:1] op_sel_hi:[1,0]
	v_pk_mul_f32 v[48:49], v[48:49], v[0:1] op_sel_hi:[1,0]
	v_pk_mul_f32 v[38:39], v[38:39], v[0:1] op_sel_hi:[1,0]
	v_pk_mul_f32 v[34:35], v[34:35], v[0:1] op_sel_hi:[1,0]
	v_pk_mul_f32 v[36:37], v[36:37], v[0:1] op_sel_hi:[1,0]
	v_pk_mul_f32 v[40:41], v[40:41], v[0:1] op_sel_hi:[1,0]
	s_waitcnt vmcnt(6)
	v_pk_mul_f32 v[46:47], v[160:161], v[46:47]
	s_waitcnt vmcnt(6)
	v_pk_mul_f32 v[50:51], v[166:167], v[44:45]
	v_pk_mul_f32 v[44:45], v[164:165], v[42:43]
	v_pk_mul_f32 v[48:49], v[162:163], v[48:49]
	v_cvt_pk_bf16_f32 v42, v46, v47
	s_nop 0
	v_cvt_pk_bf16_f32 v43, v48, v49
	v_cvt_pk_bf16_f32 v44, v44, v45
	v_cvt_pk_bf16_f32 v45, v50, v51
	global_store_dwordx4 v[58:59], v[42:45], off
	s_nop 0
	s_waitcnt vmcnt(7)
	v_pk_mul_f32 v[38:39], v[168:169], v[38:39]
	s_waitcnt vmcnt(7)
	v_pk_mul_f32 v[42:43], v[174:175], v[36:37]
	v_pk_mul_f32 v[36:37], v[172:173], v[34:35]
	v_pk_mul_f32 v[40:41], v[170:171], v[40:41]
	v_cvt_pk_bf16_f32 v34, v38, v39
	s_nop 0
	v_cvt_pk_bf16_f32 v35, v40, v41
	v_cvt_pk_bf16_f32 v36, v36, v37
	v_cvt_pk_bf16_f32 v37, v42, v43
	global_store_dwordx4 v[58:59], v[34:37], off offset:1024
	s_or_b64 exec, exec, s[14:15]
	s_andn2_b64 vcc, exec, s[6:7]
	s_cbranch_vccnz .LBB0_955
	s_branch .LBB0_1000
